# hand-written GEMM k-loop: LDS+register double buffering, saddr loads, one barrier per k-step, L2-locality tile swizzle
# speedup vs baseline: 1.0217x; 1.0217x over previous
.LBB0_1042:
	s_andn2_b32 s98, s43, 0x1ff
	s_add_i32 s99, s98, 0x200
	s_cmp_le_u32 s99, s42
	s_cbranch_scc0 .Lg_noperm
	s_and_b32 s99, s43, 7
	s_lshl_b32 s99, s99, 6
	s_add_i32 s98, s98, s99
	s_bfe_u32 s99, s43, 0x60003
	s_add_i32 s98, s98, s99
	s_branch .Lg_perm_done
.Lg_noperm:
	s_mov_b32 s98, s43
.Lg_perm_done:
	s_lshr_b32 s5, s98, 3
	s_mul_hi_u32 s6, s5, s62
	s_mul_i32 s7, s6, s45
	s_sub_i32 s5, s5, s7
	s_add_i32 s7, s6, 1
	s_sub_i32 s8, s5, s45
	s_cmp_ge_u32 s5, s45
	s_cselect_b32 s6, s7, s6
	s_cselect_b32 s5, s8, s5
	s_add_i32 s7, s6, 1
	s_cmp_ge_u32 s5, s45
	s_cselect_b32 s4, s7, s6
	s_mul_i32 s5, s4, s45
	s_lshl_b32 s5, s5, 3
	s_sub_i32 s5, s98, s5
	s_cmp_lt_u32 s4, 16
	s_cbranch_scc0 .Lg_lastgrp
	s_and_b32 s6, s5, 7
	s_lshl_b32 s4, s4, 3
	s_add_i32 s4, s4, s6
	s_lshr_b32 s10, s5, 3
	s_branch .Lg_map_done
.Lg_lastgrp:
	s_and_b32 s6, s5, 1
	s_add_i32 s4, s6, 0x80
	s_lshr_b32 s10, s5, 1
.Lg_map_done:
	s_lshl_b32 s29, s4, 7
	s_waitcnt lgkmcnt(0)
	v_add_u32_e32 v112, s29, v117
	s_lshl_b32 s63, s10, 7
	v_ashrrev_i32_e32 v103, 31, v112
	v_mul_lo_u32 v2, s26, v103
	v_mul_lo_u32 v3, s27, v112
	v_mad_u64_u32 v[0:1], s[4:5], s26, v112, 0
	v_add_u32_e32 v20, s63, v117
	v_add3_u32 v1, v1, v2, v3
	v_mad_u64_u32 v[2:3], s[4:5], v20, s28, 0
	v_ashrrev_i32_e32 v21, 31, v20
	v_mov_b32_e32 v4, v3
	v_add_u32_e32 v114, s29, v123
	v_mad_u64_u32 v[4:5], s[4:5], v21, s28, v[4:5]
	v_ashrrev_i32_e32 v105, 31, v114
	v_mov_b32_e32 v3, v4
	v_mul_lo_u32 v6, s26, v105
	v_mul_lo_u32 v7, s27, v114
	v_mad_u64_u32 v[4:5], s[4:5], s26, v114, 0
	v_add_u32_e32 v22, s63, v123
	v_add3_u32 v5, v5, v6, v7
	v_mad_u64_u32 v[6:7], s[4:5], v22, s28, 0
	v_ashrrev_i32_e32 v23, 31, v22
	v_mov_b32_e32 v8, v7
	v_add_u32_e32 v116, s29, v132
	v_mad_u64_u32 v[8:9], s[4:5], v23, s28, v[8:9]
	v_ashrrev_i32_e32 v107, 31, v116
	v_mov_b32_e32 v7, v8
	v_mul_lo_u32 v10, s26, v107
	v_mul_lo_u32 v11, s27, v116
	v_mad_u64_u32 v[8:9], s[4:5], s26, v116, 0
	v_add_u32_e32 v24, s63, v132
	v_add3_u32 v9, v9, v10, v11
	v_mad_u64_u32 v[10:11], s[4:5], v24, s28, 0
	v_ashrrev_i32_e32 v25, 31, v24
	v_mov_b32_e32 v12, v11
	v_add_u32_e32 v122, s29, v133
	v_mad_u64_u32 v[12:13], s[4:5], v25, s28, v[12:13]
	v_ashrrev_i32_e32 v109, 31, v122
	v_mov_b32_e32 v11, v12
	v_mul_lo_u32 v14, s26, v109
	v_mul_lo_u32 v15, s27, v122
	v_mad_u64_u32 v[12:13], s[4:5], s26, v122, 0
	v_add_u32_e32 v26, s63, v133
	v_add3_u32 v13, v13, v14, v15
	v_mad_u64_u32 v[14:15], s[4:5], v26, s28, 0
	v_ashrrev_i32_e32 v27, 31, v26
	v_mov_b32_e32 v18, v15
	v_mad_u64_u32 v[18:19], s[4:5], v27, s28, v[18:19]
	v_lshl_add_u64 v[0:1], v[0:1], 1, v[98:99]
	v_mov_b32_e32 v15, v18
	v_lshl_add_u64 v[2:3], v[2:3], 1, v[100:101]
	v_lshl_add_u64 v[4:5], v[4:5], 1, v[98:99]
	v_lshl_add_u64 v[6:7], v[6:7], 1, v[100:101]
	v_lshl_add_u64 v[8:9], v[8:9], 1, v[98:99]
	v_lshl_add_u64 v[10:11], v[10:11], 1, v[100:101]
	v_lshl_add_u64 v[12:13], v[12:13], 1, v[98:99]
	v_lshl_add_u64 v[14:15], v[14:15], 1, v[100:101]
	global_load_dwordx4 v[66:69], v[0:1], off
	global_load_dwordx4 v[70:73], v[2:3], off
	global_load_dwordx4 v[74:77], v[4:5], off
	global_load_dwordx4 v[78:81], v[6:7], off
	global_load_dwordx4 v[82:85], v[8:9], off
	global_load_dwordx4 v[86:89], v[10:11], off
	global_load_dwordx4 v[90:93], v[12:13], off
	global_load_dwordx4 v[94:97], v[14:15], off
	v_mov_b64_e32 v[18:19], s[92:93]
	v_mul_lo_u32 v25, s94, v25
	v_mul_lo_u32 v0, s95, v24
	v_mad_u64_u32 v[126:127], s[4:5], s94, v24, v[18:19]
	v_add3_u32 v127, v0, v127, v25
	v_mul_lo_u32 v0, s94, v23
	v_mul_lo_u32 v1, s95, v22
	v_mad_u64_u32 v[128:129], s[4:5], s94, v22, v[18:19]
	v_add3_u32 v129, v1, v129, v0
	v_mul_lo_u32 v0, s94, v21
	v_mul_lo_u32 v1, s95, v20
	v_mad_u64_u32 v[130:131], s[4:5], s94, v20, v[18:19]
	v_mul_lo_u32 v27, s94, v27
	v_mul_lo_u32 v28, s95, v26
	v_mad_u64_u32 v[124:125], s[4:5], s94, v26, v[18:19]
	v_add3_u32 v131, v1, v131, v0
	v_mov_b32_e32 v0, 0
	v_add3_u32 v125, v28, v125, v27
	s_mov_b32 s6, 64
	v_mov_b32_e32 v1, v0
	v_mov_b32_e32 v2, v0
	v_mov_b32_e32 v3, v0
	v_mov_b32_e32 v4, v0
	v_mov_b32_e32 v5, v0
	v_mov_b32_e32 v6, v0
	v_mov_b32_e32 v7, v0
	v_mov_b32_e32 v8, v0
	v_mov_b32_e32 v9, v0
	v_mov_b32_e32 v10, v0
	v_mov_b32_e32 v11, v0
	v_mov_b32_e32 v12, v0
	v_mov_b32_e32 v13, v0
	v_mov_b32_e32 v14, v0
	v_mov_b32_e32 v15, v0
	v_mov_b32_e32 v18, v0
	v_mov_b32_e32 v19, v0
	v_mov_b32_e32 v20, v0
	v_mov_b32_e32 v21, v0
	v_mov_b32_e32 v22, v0
	v_mov_b32_e32 v23, v0
	v_mov_b32_e32 v24, v0
	v_mov_b32_e32 v25, v0
	v_mov_b32_e32 v26, v0
	v_mov_b32_e32 v27, v0
	v_mov_b32_e32 v28, v0
	v_mov_b32_e32 v29, v0
	v_mov_b32_e32 v30, v0
	v_mov_b32_e32 v31, v0
	v_mov_b32_e32 v32, v0
	v_mov_b32_e32 v33, v0
	v_mov_b32_e32 v34, v0
	v_mov_b32_e32 v35, v0
	v_mov_b32_e32 v36, v0
	v_mov_b32_e32 v37, v0
	v_mov_b32_e32 v38, v0
	v_mov_b32_e32 v39, v0
	v_mov_b32_e32 v40, v0
	v_mov_b32_e32 v41, v0
	v_mov_b32_e32 v42, v0
	v_mov_b32_e32 v43, v0
	v_mov_b32_e32 v44, v0
	v_mov_b32_e32 v45, v0
	v_mov_b32_e32 v46, v0
	v_mov_b32_e32 v47, v0
	v_mov_b32_e32 v48, v0
	v_mov_b32_e32 v49, v0
	v_mov_b32_e32 v50, v0
	v_mov_b32_e32 v51, v0
	v_mov_b32_e32 v52, v0
	v_mov_b32_e32 v53, v0
	v_mov_b32_e32 v54, v0
	v_mov_b32_e32 v55, v0
	v_mov_b32_e32 v56, v0
	v_mov_b32_e32 v57, v0
	v_mov_b32_e32 v58, v0
	v_mov_b32_e32 v59, v0
	v_mov_b32_e32 v60, v0
	v_mov_b32_e32 v61, v0
	v_mov_b32_e32 v62, v0
	v_mov_b32_e32 v63, v0
	v_mov_b32_e32 v64, v0
	v_mov_b32_e32 v65, v0
	s_branch .Lg_pro
.Lg_pro:
	v_add_u32_e32 v124, s63, v117
	v_add_u32_e32 v125, s63, v123
	v_add_u32_e32 v126, s63, v132
	v_add_u32_e32 v127, s63, v133
	v_mul_lo_u32 v124, v124, s94
	v_mul_lo_u32 v125, v125, s94
	v_mul_lo_u32 v126, v126, s94
	v_mul_lo_u32 v127, v127, s94
	v_add_u32_e32 v124, v124, v110
	v_add_u32_e32 v125, v125, v110
	v_add_u32_e32 v126, v126, v110
	v_add_u32_e32 v127, v127, v110
	s_lshl_b32 s98, s26, 1
	v_mul_lo_u32 v128, v112, s98
	v_mul_lo_u32 v129, v114, s98
	v_mul_lo_u32 v130, v116, s98
	v_mul_lo_u32 v131, v122, s98
	v_add_u32_e32 v128, v128, v16
	v_add_u32_e32 v129, v129, v16
	v_add_u32_e32 v130, v130, v16
	v_add_u32_e32 v131, v131, v16
	s_cmp_eq_u32 s6, s44
	s_cbranch_scc0 .Lg_nsw_pro
	v_lshlrev_b32_e32 v128, 11, v112
	v_lshlrev_b32_e32 v129, 11, v114
	v_lshlrev_b32_e32 v130, 11, v116
	v_lshlrev_b32_e32 v131, 11, v122
	v_add_u32_e32 v128, v128, v16
	v_add_u32_e32 v129, v129, v16
	v_add_u32_e32 v130, v130, v16
	v_add_u32_e32 v131, v131, v16
.Lg_nsw_pro:
	s_cmp_lt_u32 s6, s44
	s_cselect_b32 s99, s25, s23
	s_cselect_b32 s98, s24, s22
	s_sub_i32 s8, s6, s44
	s_min_u32 s52, s6, s8
	s_lshl_b32 s8, s52, 1
	s_add_u32 s98, s98, s8
	s_addc_u32 s99, s99, 0
	s_sub_i32 s8, s6, 64
	s_lshl_b32 s8, s8, 1
	s_add_u32 s8, s92, s8
	s_addc_u32 s9, s93, 0
	global_load_dwordx4 v[156:159], v128, s[98:99]
	global_load_dwordx4 v[160:163], v124, s[8:9]
	global_load_dwordx4 v[164:167], v129, s[98:99]
	global_load_dwordx4 v[168:171], v125, s[8:9]
	global_load_dwordx4 v[172:175], v130, s[98:99]
	global_load_dwordx4 v[176:179], v126, s[8:9]
	global_load_dwordx4 v[180:183], v131, s[98:99]
	global_load_dwordx4 v[184:187], v127, s[8:9]
	s_add_i32 s6, s6, 64
	s_mov_b32 s11, 0
	s_waitcnt vmcnt(8)
	ds_write_b128 v102, v[66:69]
	ds_write_b128 v102, v[70:73] offset:18432
	ds_write_b128 v104, v[74:77]
	ds_write_b128 v104, v[78:81] offset:18432
	ds_write_b128 v106, v[82:85]
	ds_write_b128 v106, v[86:89] offset:18432
	ds_write_b128 v108, v[90:93]
	ds_write_b128 v108, v[94:97] offset:18432
	s_waitcnt lgkmcnt(0)
	s_barrier
.Lg_A:
	ds_read_b128 v[136:139], v134
	ds_read_b128 v[152:155], v135 offset:18432
	ds_read_b128 v[188:191], v135 offset:20736
	ds_read_b128 v[192:195], v135 offset:23040
	ds_read_b128 v[196:199], v135 offset:25344
	ds_read_b128 v[140:143], v134 offset:2304
	ds_read_b128 v[144:147], v134 offset:4608
	ds_read_b128 v[148:151], v134 offset:6912
	s_cmp_lt_u32 s6, s28
	s_cselect_b32 s7, 1, 0
	s_cbranch_scc0 .Lg_A_nl
	s_cmp_eq_u32 s6, s44
	s_cbranch_scc0 .Lg_nsw_A
	v_lshlrev_b32_e32 v128, 11, v112
	v_lshlrev_b32_e32 v129, 11, v114
	v_lshlrev_b32_e32 v130, 11, v116
	v_lshlrev_b32_e32 v131, 11, v122
	v_add_u32_e32 v128, v128, v16
	v_add_u32_e32 v129, v129, v16
	v_add_u32_e32 v130, v130, v16
	v_add_u32_e32 v131, v131, v16
.Lg_nsw_A:
	s_cmp_lt_u32 s6, s44
	s_cselect_b32 s99, s25, s23
	s_cselect_b32 s98, s24, s22
	s_sub_i32 s8, s6, s44
	s_min_u32 s52, s6, s8
	s_lshl_b32 s8, s52, 1
	s_add_u32 s98, s98, s8
	s_addc_u32 s99, s99, 0
	s_sub_i32 s8, s6, 64
	s_lshl_b32 s8, s8, 1
	s_add_u32 s8, s92, s8
	s_addc_u32 s9, s93, 0
	global_load_dwordx4 v[66:69], v128, s[98:99]
	global_load_dwordx4 v[70:73], v124, s[8:9]
	global_load_dwordx4 v[74:77], v129, s[98:99]
	global_load_dwordx4 v[78:81], v125, s[8:9]
	global_load_dwordx4 v[82:85], v130, s[98:99]
	global_load_dwordx4 v[86:89], v126, s[8:9]
	global_load_dwordx4 v[90:93], v131, s[98:99]
	global_load_dwordx4 v[94:97], v127, s[8:9]
	s_add_i32 s6, s6, 64
.Lg_A_nl:
	s_waitcnt lgkmcnt(3)
	v_mfma_f32_16x16x32_bf16 v[62:65], v[136:139], v[152:155], v[62:65]
	v_mfma_f32_16x16x32_bf16 v[58:61], v[136:139], v[188:191], v[58:61]
	v_mfma_f32_16x16x32_bf16 v[54:57], v[136:139], v[192:195], v[54:57]
	v_mfma_f32_16x16x32_bf16 v[50:53], v[136:139], v[196:199], v[50:53]
	ds_read_b128 v[200:203], v134 offset:64
	ds_read_b128 v[220:223], v135 offset:18496
	ds_read_b128 v[230:233], v135 offset:20800
	ds_read_b128 v[234:237], v135 offset:23104
	ds_read_b128 v[244:247], v135 offset:25408
	ds_read_b128 v[204:207], v134 offset:2368
	ds_read_b128 v[212:215], v134 offset:4672
	ds_read_b128 v[216:219], v134 offset:6976
	s_waitcnt lgkmcnt(10)
	v_mfma_f32_16x16x32_bf16 v[46:49], v[140:143], v[152:155], v[46:49]
	v_mfma_f32_16x16x32_bf16 v[42:45], v[140:143], v[188:191], v[42:45]
	v_mfma_f32_16x16x32_bf16 v[38:41], v[140:143], v[192:195], v[38:41]
	v_mfma_f32_16x16x32_bf16 v[34:37], v[140:143], v[196:199], v[34:37]
	s_waitcnt lgkmcnt(9)
	v_mfma_f32_16x16x32_bf16 v[30:33], v[144:147], v[152:155], v[30:33]
	v_mfma_f32_16x16x32_bf16 v[26:29], v[144:147], v[188:191], v[26:29]
	v_mfma_f32_16x16x32_bf16 v[22:25], v[144:147], v[192:195], v[22:25]
	v_mfma_f32_16x16x32_bf16 v[18:21], v[144:147], v[196:199], v[18:21]
	s_waitcnt lgkmcnt(8)
	v_mfma_f32_16x16x32_bf16 v[12:15], v[148:151], v[152:155], v[12:15]
	v_mfma_f32_16x16x32_bf16 v[8:11], v[148:151], v[188:191], v[8:11]
	v_mfma_f32_16x16x32_bf16 v[4:7], v[148:151], v[192:195], v[4:7]
	v_mfma_f32_16x16x32_bf16 v[0:3], v[148:151], v[196:199], v[0:3]
	s_waitcnt lgkmcnt(3)
	v_mfma_f32_16x16x32_bf16 v[62:65], v[200:203], v[220:223], v[62:65]
	v_mfma_f32_16x16x32_bf16 v[58:61], v[200:203], v[230:233], v[58:61]
	v_mfma_f32_16x16x32_bf16 v[54:57], v[200:203], v[234:237], v[54:57]
	v_mfma_f32_16x16x32_bf16 v[50:53], v[200:203], v[244:247], v[50:53]
	s_waitcnt lgkmcnt(2)
	v_mfma_f32_16x16x32_bf16 v[46:49], v[204:207], v[220:223], v[46:49]
	v_mfma_f32_16x16x32_bf16 v[42:45], v[204:207], v[230:233], v[42:45]
	v_mfma_f32_16x16x32_bf16 v[38:41], v[204:207], v[234:237], v[38:41]
	v_mfma_f32_16x16x32_bf16 v[34:37], v[204:207], v[244:247], v[34:37]
	s_waitcnt lgkmcnt(1)
	v_mfma_f32_16x16x32_bf16 v[30:33], v[212:215], v[220:223], v[30:33]
	v_mfma_f32_16x16x32_bf16 v[26:29], v[212:215], v[230:233], v[26:29]
	v_mfma_f32_16x16x32_bf16 v[22:25], v[212:215], v[234:237], v[22:25]
	v_mfma_f32_16x16x32_bf16 v[18:21], v[212:215], v[244:247], v[18:21]
	s_waitcnt lgkmcnt(0)
	v_mfma_f32_16x16x32_bf16 v[12:15], v[216:219], v[220:223], v[12:15]
	v_mfma_f32_16x16x32_bf16 v[8:11], v[216:219], v[230:233], v[8:11]
	v_mfma_f32_16x16x32_bf16 v[4:7], v[216:219], v[234:237], v[4:7]
	v_mfma_f32_16x16x32_bf16 v[0:3], v[216:219], v[244:247], v[0:3]
	s_add_i32 s11, s11, 64
	s_cmp_ge_u32 s11, s28
	s_cbranch_scc1 .Lg_exit
	s_cmp_eq_u32 s7, 0
	s_cbranch_scc1 .Lg_A_w0
	s_waitcnt vmcnt(8)
	s_branch .Lg_A_w

.Lg_A_w:
	ds_write_b128 v102, v[156:159] offset:36864
	ds_write_b128 v102, v[160:163] offset:55296
	ds_write_b128 v104, v[164:167] offset:36864
	ds_write_b128 v104, v[168:171] offset:55296
	ds_write_b128 v106, v[172:175] offset:36864
	ds_write_b128 v106, v[176:179] offset:55296
	ds_write_b128 v108, v[180:183] offset:36864
	ds_write_b128 v108, v[184:187] offset:55296
	s_waitcnt lgkmcnt(0)
	s_barrier
.Lg_B:
	ds_read_b128 v[136:139], v134 offset:36864
	ds_read_b128 v[152:155], v135 offset:55296
	ds_read_b128 v[188:191], v135 offset:57600
	ds_read_b128 v[192:195], v135 offset:59904
	ds_read_b128 v[196:199], v135 offset:62208
	ds_read_b128 v[140:143], v134 offset:39168
	ds_read_b128 v[144:147], v134 offset:41472
	ds_read_b128 v[148:151], v134 offset:43776
	s_cmp_lt_u32 s6, s28
	s_cselect_b32 s7, 1, 0
	s_cbranch_scc0 .Lg_B_nl
	s_cmp_eq_u32 s6, s44
	s_cbranch_scc0 .Lg_nsw_B
	v_lshlrev_b32_e32 v128, 11, v112
	v_lshlrev_b32_e32 v129, 11, v114
	v_lshlrev_b32_e32 v130, 11, v116
	v_lshlrev_b32_e32 v131, 11, v122
	v_add_u32_e32 v128, v128, v16
	v_add_u32_e32 v129, v129, v16
	v_add_u32_e32 v130, v130, v16
	v_add_u32_e32 v131, v131, v16
.Lg_nsw_B:
	s_cmp_lt_u32 s6, s44
	s_cselect_b32 s99, s25, s23
	s_cselect_b32 s98, s24, s22
	s_sub_i32 s8, s6, s44
	s_min_u32 s52, s6, s8
	s_lshl_b32 s8, s52, 1
	s_add_u32 s98, s98, s8
	s_addc_u32 s99, s99, 0
	s_sub_i32 s8, s6, 64
	s_lshl_b32 s8, s8, 1
	s_add_u32 s8, s92, s8
	s_addc_u32 s9, s93, 0
	global_load_dwordx4 v[156:159], v128, s[98:99]
	global_load_dwordx4 v[160:163], v124, s[8:9]
	global_load_dwordx4 v[164:167], v129, s[98:99]
	global_load_dwordx4 v[168:171], v125, s[8:9]
	global_load_dwordx4 v[172:175], v130, s[98:99]
	global_load_dwordx4 v[176:179], v126, s[8:9]
	global_load_dwordx4 v[180:183], v131, s[98:99]
	global_load_dwordx4 v[184:187], v127, s[8:9]
	s_add_i32 s6, s6, 64
.Lg_B_nl:
	s_waitcnt lgkmcnt(3)
	v_mfma_f32_16x16x32_bf16 v[62:65], v[136:139], v[152:155], v[62:65]
	v_mfma_f32_16x16x32_bf16 v[58:61], v[136:139], v[188:191], v[58:61]
	v_mfma_f32_16x16x32_bf16 v[54:57], v[136:139], v[192:195], v[54:57]
	v_mfma_f32_16x16x32_bf16 v[50:53], v[136:139], v[196:199], v[50:53]
	ds_read_b128 v[200:203], v134 offset:36928
	ds_read_b128 v[220:223], v135 offset:55360
	ds_read_b128 v[230:233], v135 offset:57664
	ds_read_b128 v[234:237], v135 offset:59968
	ds_read_b128 v[244:247], v135 offset:62272
	ds_read_b128 v[204:207], v134 offset:39232
	ds_read_b128 v[212:215], v134 offset:41536
	ds_read_b128 v[216:219], v134 offset:43840
	s_waitcnt lgkmcnt(10)
	v_mfma_f32_16x16x32_bf16 v[46:49], v[140:143], v[152:155], v[46:49]
	v_mfma_f32_16x16x32_bf16 v[42:45], v[140:143], v[188:191], v[42:45]
	v_mfma_f32_16x16x32_bf16 v[38:41], v[140:143], v[192:195], v[38:41]
	v_mfma_f32_16x16x32_bf16 v[34:37], v[140:143], v[196:199], v[34:37]
	s_waitcnt lgkmcnt(9)
	v_mfma_f32_16x16x32_bf16 v[30:33], v[144:147], v[152:155], v[30:33]
	v_mfma_f32_16x16x32_bf16 v[26:29], v[144:147], v[188:191], v[26:29]
	v_mfma_f32_16x16x32_bf16 v[22:25], v[144:147], v[192:195], v[22:25]
	v_mfma_f32_16x16x32_bf16 v[18:21], v[144:147], v[196:199], v[18:21]
	s_waitcnt lgkmcnt(8)
	v_mfma_f32_16x16x32_bf16 v[12:15], v[148:151], v[152:155], v[12:15]
	v_mfma_f32_16x16x32_bf16 v[8:11], v[148:151], v[188:191], v[8:11]
	v_mfma_f32_16x16x32_bf16 v[4:7], v[148:151], v[192:195], v[4:7]
	v_mfma_f32_16x16x32_bf16 v[0:3], v[148:151], v[196:199], v[0:3]
	s_waitcnt lgkmcnt(3)
	v_mfma_f32_16x16x32_bf16 v[62:65], v[200:203], v[220:223], v[62:65]
	v_mfma_f32_16x16x32_bf16 v[58:61], v[200:203], v[230:233], v[58:61]
	v_mfma_f32_16x16x32_bf16 v[54:57], v[200:203], v[234:237], v[54:57]
	v_mfma_f32_16x16x32_bf16 v[50:53], v[200:203], v[244:247], v[50:53]
	s_waitcnt lgkmcnt(2)
	v_mfma_f32_16x16x32_bf16 v[46:49], v[204:207], v[220:223], v[46:49]
	v_mfma_f32_16x16x32_bf16 v[42:45], v[204:207], v[230:233], v[42:45]
	v_mfma_f32_16x16x32_bf16 v[38:41], v[204:207], v[234:237], v[38:41]
	v_mfma_f32_16x16x32_bf16 v[34:37], v[204:207], v[244:247], v[34:37]
	s_waitcnt lgkmcnt(1)
	v_mfma_f32_16x16x32_bf16 v[30:33], v[212:215], v[220:223], v[30:33]
	v_mfma_f32_16x16x32_bf16 v[26:29], v[212:215], v[230:233], v[26:29]
	v_mfma_f32_16x16x32_bf16 v[22:25], v[212:215], v[234:237], v[22:25]
	v_mfma_f32_16x16x32_bf16 v[18:21], v[212:215], v[244:247], v[18:21]
	s_waitcnt lgkmcnt(0)
	v_mfma_f32_16x16x32_bf16 v[12:15], v[216:219], v[220:223], v[12:15]
	v_mfma_f32_16x16x32_bf16 v[8:11], v[216:219], v[230:233], v[8:11]
	v_mfma_f32_16x16x32_bf16 v[4:7], v[216:219], v[234:237], v[4:7]
	v_mfma_f32_16x16x32_bf16 v[0:3], v[216:219], v[244:247], v[0:3]
	s_add_i32 s11, s11, 64
	s_cmp_ge_u32 s11, s28
	s_cbranch_scc1 .Lg_exit
	s_cmp_eq_u32 s7, 0
	s_cbranch_scc1 .Lg_B_w0
	s_waitcnt vmcnt(8)
	s_branch .Lg_B_w

.Lg_B_w:
	ds_write_b128 v102, v[66:69]
	ds_write_b128 v102, v[70:73] offset:18432
	ds_write_b128 v104, v[74:77]
	ds_write_b128 v104, v[78:81] offset:18432
	ds_write_b128 v106, v[82:85]
	ds_write_b128 v106, v[86:89] offset:18432
	ds_write_b128 v108, v[90:93]
	ds_write_b128 v108, v[94:97] offset:18432
	s_waitcnt lgkmcnt(0)
	s_barrier
	s_branch .Lg_A
.Lg_exit:
	s_nop 7
